# GEMM k-loops: ds_write waits cover only the older register set (vmcnt(8) in steady state), compiler's conservative waits on the in-flight prefetch removed
# speedup vs baseline: 1.0324x; 1.0048x over previous
.LBB0_127:
	s_cmp_lt_u32 s11, 14
	s_cselect_b64 s[14:15], -1, 0
	s_cmp_gt_u32 s11, 13
	v_lshl_add_u64 v[164:165], v[134:135], 0, s[12:13]
	v_lshl_add_u64 v[162:163], v[132:133], 0, s[12:13]
	s_cbranch_scc1 .LBB0_129
	v_add_co_u32_e32 v80, vcc, 0x10000, v164
	global_load_dwordx4 v[64:67], v[164:165], off offset:256
	global_load_dwordx4 v[72:75], v[162:163], off offset:256
	v_addc_co_u32_e32 v81, vcc, 0, v165, vcc
	v_add_co_u32_e32 v88, vcc, 0x10000, v162
	global_load_dwordx4 v[80:83], v[80:81], off offset:256
	s_nop 0
	v_addc_co_u32_e32 v89, vcc, 0, v163, vcc
	v_add_co_u32_e32 v96, vcc, 0x20000, v164
	global_load_dwordx4 v[88:91], v[88:89], off offset:256
	s_nop 0
	v_addc_co_u32_e32 v97, vcc, 0, v165, vcc
	v_add_co_u32_e32 v104, vcc, 0x20000, v162
	global_load_dwordx4 v[96:99], v[96:97], off offset:256
	s_nop 0
	v_addc_co_u32_e32 v105, vcc, 0, v163, vcc
	v_add_co_u32_e32 v112, vcc, 0x30000, v164
	global_load_dwordx4 v[104:107], v[104:105], off offset:256
	s_nop 0
	v_addc_co_u32_e32 v113, vcc, 0, v165, vcc
	v_add_co_u32_e32 v124, vcc, 0x30000, v162
	global_load_dwordx4 v[112:115], v[112:113], off offset:256
	s_nop 0
	v_addc_co_u32_e32 v125, vcc, 0, v163, vcc
	global_load_dwordx4 v[124:127], v[124:125], off offset:256
.LBB0_129:
	ds_read_b128 v[174:177], v140
	ds_read_b128 v[178:181], v131 offset:18432
	ds_read_b128 v[182:185], v140 offset:32
	ds_read_b128 v[186:189], v131 offset:18464
	ds_read_b128 v[190:193], v131 offset:23040
	ds_read_b128 v[194:197], v131 offset:23072
	s_cmp_gt_u32 s11, 12
	s_waitcnt lgkmcnt(4)
	v_mfma_f32_32x32x16_bf16 v[48:63], v[174:177], v[178:181], v[48:63]
	s_waitcnt lgkmcnt(1)
	v_mfma_f32_32x32x16_bf16 v[16:31], v[174:177], v[190:193], v[16:31]
	ds_read_b128 v[174:177], v140 offset:4608
	ds_read_b128 v[198:201], v140 offset:4640
	s_waitcnt lgkmcnt(1)
	v_mfma_f32_32x32x16_bf16 v[32:47], v[174:177], v[178:181], v[32:47]
	v_mfma_f32_32x32x16_bf16 v[0:15], v[174:177], v[190:193], v[0:15]
	v_mfma_f32_32x32x16_bf16 v[48:63], v[182:185], v[186:189], v[48:63]
	v_mfma_f32_32x32x16_bf16 v[16:31], v[182:185], v[194:197], v[16:31]
	s_waitcnt lgkmcnt(0)
	v_mfma_f32_32x32x16_bf16 v[32:47], v[198:201], v[186:189], v[32:47]
	ds_read_b128 v[174:177], v140 offset:64
	ds_read_b128 v[178:181], v131 offset:18496
	ds_read_b128 v[182:185], v140 offset:96
	ds_read_b128 v[186:189], v131 offset:18528
	v_mfma_f32_32x32x16_bf16 v[0:15], v[198:201], v[194:197], v[0:15]
	ds_read_b128 v[190:193], v131 offset:23104
	ds_read_b128 v[194:197], v131 offset:23136
	s_waitcnt lgkmcnt(4)
	v_mfma_f32_32x32x16_bf16 v[48:63], v[174:177], v[178:181], v[48:63]
	s_waitcnt lgkmcnt(1)
	v_mfma_f32_32x32x16_bf16 v[16:31], v[174:177], v[190:193], v[16:31]
	ds_read_b128 v[174:177], v140 offset:4672
	ds_read_b128 v[198:201], v140 offset:4704
	s_waitcnt lgkmcnt(0)
	s_barrier
	s_cmp_lt_u32 s11, 14
	s_cbranch_scc1 .Lgw0
	s_waitcnt vmcnt(0)
.Lgw0:
	s_waitcnt vmcnt(8)
	s_cmp_gt_u32 s11, 12
	ds_write_b128 v130, v[68:71]
	ds_write_b128 v130, v[76:79] offset:18432
	ds_write_b128 v130, v[84:87] offset:4608
	ds_write_b128 v130, v[92:95] offset:23040
	ds_write_b128 v130, v[100:103] offset:9216
	ds_write_b128 v130, v[108:111] offset:27648
	ds_write_b128 v130, v[116:119] offset:13824
	ds_write_b128 v130, v[120:123] offset:32256
	s_waitcnt lgkmcnt(0)
	v_mfma_f32_32x32x16_bf16 v[32:47], v[174:177], v[178:181], v[32:47]
	s_barrier
	v_mfma_f32_32x32x16_bf16 v[0:15], v[174:177], v[190:193], v[0:15]
	v_mfma_f32_32x32x16_bf16 v[48:63], v[182:185], v[186:189], v[48:63]
	v_mfma_f32_32x32x16_bf16 v[16:31], v[182:185], v[194:197], v[16:31]
	v_mfma_f32_32x32x16_bf16 v[32:47], v[198:201], v[186:189], v[32:47]
	v_mfma_f32_32x32x16_bf16 v[0:15], v[198:201], v[194:197], v[0:15]
	s_cbranch_scc1 .LBB0_131
	v_add_co_u32_e32 v84, vcc, 0x10000, v164
	global_load_dwordx4 v[68:71], v[164:165], off offset:384
	global_load_dwordx4 v[76:79], v[162:163], off offset:384
	v_addc_co_u32_e32 v85, vcc, 0, v165, vcc
	v_add_co_u32_e32 v92, vcc, 0x10000, v162
	global_load_dwordx4 v[84:87], v[84:85], off offset:384
	s_nop 0
	v_addc_co_u32_e32 v93, vcc, 0, v163, vcc
	v_add_co_u32_e32 v100, vcc, 0x20000, v164
	global_load_dwordx4 v[92:95], v[92:93], off offset:384
	s_nop 0
	v_addc_co_u32_e32 v101, vcc, 0, v165, vcc
	v_add_co_u32_e32 v108, vcc, 0x20000, v162
	global_load_dwordx4 v[100:103], v[100:101], off offset:384
	s_nop 0
	v_addc_co_u32_e32 v109, vcc, 0, v163, vcc
	v_add_co_u32_e32 v116, vcc, 0x30000, v164
	global_load_dwordx4 v[108:111], v[108:109], off offset:384
	s_nop 0
	v_addc_co_u32_e32 v117, vcc, 0, v165, vcc
	v_add_co_u32_e32 v120, vcc, 0x30000, v162
	global_load_dwordx4 v[116:119], v[116:117], off offset:384
	s_nop 0
	v_addc_co_u32_e32 v121, vcc, 0, v163, vcc
	global_load_dwordx4 v[120:123], v[120:121], off offset:384
.LBB0_131:
	ds_read_b128 v[162:165], v140
	ds_read_b128 v[174:177], v131 offset:18432
	ds_read_b128 v[178:181], v140 offset:32
	ds_read_b128 v[182:185], v131 offset:18464
	ds_read_b128 v[186:189], v131 offset:23040
	ds_read_b128 v[190:193], v131 offset:23072
	s_mov_b64 s[16:17], -1
	s_waitcnt lgkmcnt(4)
	v_mfma_f32_32x32x16_bf16 v[48:63], v[162:165], v[174:177], v[48:63]
	s_andn2_b64 vcc, exec, s[14:15]
	s_waitcnt lgkmcnt(1)
	v_mfma_f32_32x32x16_bf16 v[16:31], v[162:165], v[186:189], v[16:31]
	ds_read_b128 v[162:165], v140 offset:4608
	ds_read_b128 v[194:197], v140 offset:4640
	s_waitcnt lgkmcnt(1)
	v_mfma_f32_32x32x16_bf16 v[32:47], v[162:165], v[174:177], v[32:47]
	v_mfma_f32_32x32x16_bf16 v[0:15], v[162:165], v[186:189], v[0:15]
	v_mfma_f32_32x32x16_bf16 v[48:63], v[178:181], v[182:185], v[48:63]
	v_mfma_f32_32x32x16_bf16 v[16:31], v[178:181], v[190:193], v[16:31]
	s_waitcnt lgkmcnt(0)
	v_mfma_f32_32x32x16_bf16 v[32:47], v[194:197], v[182:185], v[32:47]
	ds_read_b128 v[162:165], v140 offset:64
	ds_read_b128 v[174:177], v131 offset:18496
	ds_read_b128 v[178:181], v140 offset:96
	ds_read_b128 v[182:185], v131 offset:18528
	v_mfma_f32_32x32x16_bf16 v[0:15], v[194:197], v[190:193], v[0:15]
	ds_read_b128 v[186:189], v131 offset:23104
	ds_read_b128 v[190:193], v131 offset:23136
	s_waitcnt lgkmcnt(4)
	v_mfma_f32_32x32x16_bf16 v[48:63], v[162:165], v[174:177], v[48:63]
	s_waitcnt lgkmcnt(1)
	v_mfma_f32_32x32x16_bf16 v[16:31], v[162:165], v[186:189], v[16:31]
	ds_read_b128 v[162:165], v140 offset:4672
	ds_read_b128 v[194:197], v140 offset:4704
	s_waitcnt lgkmcnt(0)
	s_barrier
	v_mfma_f32_32x32x16_bf16 v[32:47], v[162:165], v[174:177], v[32:47]
	v_mfma_f32_32x32x16_bf16 v[0:15], v[162:165], v[186:189], v[0:15]
	v_mfma_f32_32x32x16_bf16 v[48:63], v[178:181], v[182:185], v[48:63]
	v_mfma_f32_32x32x16_bf16 v[16:31], v[178:181], v[190:193], v[16:31]
	v_mfma_f32_32x32x16_bf16 v[32:47], v[194:197], v[182:185], v[32:47]
	v_mfma_f32_32x32x16_bf16 v[0:15], v[194:197], v[190:193], v[0:15]
	s_cbranch_vccnz .LBB0_126
	s_add_u32 s12, s12, 0x100
	s_waitcnt vmcnt(8)
	ds_write_b128 v130, v[64:67]
	ds_write_b128 v130, v[72:75] offset:18432
	ds_write_b128 v130, v[80:83] offset:4608
	ds_write_b128 v130, v[88:91] offset:23040
	ds_write_b128 v130, v[96:99] offset:9216
	ds_write_b128 v130, v[104:107] offset:27648
	ds_write_b128 v130, v[112:115] offset:13824
	ds_write_b128 v130, v[124:127] offset:32256
	s_waitcnt lgkmcnt(0)
	s_barrier
	s_addc_u32 s13, s13, 0
	s_add_i32 s11, s11, 2
	s_mov_b64 s[16:17], 0
	s_branch .LBB0_126

.LBB0_373:
	s_cmp_lt_u32 s12, 14
	s_cselect_b64 s[6:7], -1, 0
	s_cmp_gt_u32 s12, 13
	v_lshl_add_u64 v[144:145], v[134:135], 0, s[4:5]
	v_lshl_add_u64 v[142:143], v[132:133], 0, s[4:5]
	s_cbranch_scc1 .LBB0_375
	v_add_co_u32_e32 v80, vcc, 0x10000, v144
	global_load_dwordx4 v[64:67], v[144:145], off offset:256
	global_load_dwordx4 v[72:75], v[142:143], off offset:256
	v_addc_co_u32_e32 v81, vcc, 0, v145, vcc
	v_add_co_u32_e32 v88, vcc, 0x10000, v142
	global_load_dwordx4 v[80:83], v[80:81], off offset:256
	s_nop 0
	v_addc_co_u32_e32 v89, vcc, 0, v143, vcc
	v_add_co_u32_e32 v96, vcc, 0x20000, v144
	global_load_dwordx4 v[88:91], v[88:89], off offset:256
	s_nop 0
	v_addc_co_u32_e32 v97, vcc, 0, v145, vcc
	v_add_co_u32_e32 v104, vcc, 0x20000, v142
	global_load_dwordx4 v[96:99], v[96:97], off offset:256
	s_nop 0
	v_addc_co_u32_e32 v105, vcc, 0, v143, vcc
	v_add_co_u32_e32 v112, vcc, 0x30000, v144
	global_load_dwordx4 v[104:107], v[104:105], off offset:256
	s_nop 0
	v_addc_co_u32_e32 v113, vcc, 0, v145, vcc
	v_add_co_u32_e32 v124, vcc, 0x30000, v142
	global_load_dwordx4 v[112:115], v[112:113], off offset:256
	s_nop 0
	v_addc_co_u32_e32 v125, vcc, 0, v143, vcc
	global_load_dwordx4 v[124:127], v[124:125], off offset:256
.LBB0_375:
	ds_read_b128 v[148:151], v140
	ds_read_b128 v[152:155], v141 offset:18432
	ds_read_b128 v[156:159], v140 offset:32
	ds_read_b128 v[160:163], v141 offset:18464
	ds_read_b128 v[164:167], v141 offset:23040
	ds_read_b128 v[168:171], v141 offset:23072
	s_cmp_gt_u32 s12, 12
	s_waitcnt lgkmcnt(4)
	v_mfma_f32_32x32x16_bf16 v[48:63], v[148:151], v[152:155], v[48:63]
	s_waitcnt lgkmcnt(1)
	v_mfma_f32_32x32x16_bf16 v[16:31], v[148:151], v[164:167], v[16:31]
	ds_read_b128 v[148:151], v140 offset:4608
	ds_read_b128 v[172:175], v140 offset:4640
	s_waitcnt lgkmcnt(1)
	v_mfma_f32_32x32x16_bf16 v[32:47], v[148:151], v[152:155], v[32:47]
	v_mfma_f32_32x32x16_bf16 v[0:15], v[148:151], v[164:167], v[0:15]
	v_mfma_f32_32x32x16_bf16 v[48:63], v[156:159], v[160:163], v[48:63]
	v_mfma_f32_32x32x16_bf16 v[16:31], v[156:159], v[168:171], v[16:31]
	s_waitcnt lgkmcnt(0)
	v_mfma_f32_32x32x16_bf16 v[32:47], v[172:175], v[160:163], v[32:47]
	ds_read_b128 v[148:151], v140 offset:64
	ds_read_b128 v[152:155], v141 offset:18496
	ds_read_b128 v[156:159], v140 offset:96
	ds_read_b128 v[160:163], v141 offset:18528
	v_mfma_f32_32x32x16_bf16 v[0:15], v[172:175], v[168:171], v[0:15]
	ds_read_b128 v[164:167], v141 offset:23104
	ds_read_b128 v[168:171], v141 offset:23136
	s_waitcnt lgkmcnt(4)
	v_mfma_f32_32x32x16_bf16 v[48:63], v[148:151], v[152:155], v[48:63]
	s_waitcnt lgkmcnt(1)
	v_mfma_f32_32x32x16_bf16 v[16:31], v[148:151], v[164:167], v[16:31]
	ds_read_b128 v[148:151], v140 offset:4672
	ds_read_b128 v[172:175], v140 offset:4704
	s_waitcnt lgkmcnt(0)
	s_barrier
	s_cmp_lt_u32 s12, 14
	s_cbranch_scc1 .Lgw1
	s_waitcnt vmcnt(0)
.Lgw1:
	s_waitcnt vmcnt(8)
	s_cmp_gt_u32 s12, 12
	ds_write_b128 v130, v[68:71]
	ds_write_b128 v130, v[76:79] offset:18432
	ds_write_b128 v130, v[84:87] offset:4608
	ds_write_b128 v130, v[92:95] offset:23040
	ds_write_b128 v130, v[100:103] offset:9216
	ds_write_b128 v130, v[108:111] offset:27648
	ds_write_b128 v130, v[116:119] offset:13824
	ds_write_b128 v130, v[120:123] offset:32256
	s_waitcnt lgkmcnt(0)
	v_mfma_f32_32x32x16_bf16 v[32:47], v[148:151], v[152:155], v[32:47]
	s_barrier
	v_mfma_f32_32x32x16_bf16 v[0:15], v[148:151], v[164:167], v[0:15]
	v_mfma_f32_32x32x16_bf16 v[48:63], v[156:159], v[160:163], v[48:63]
	v_mfma_f32_32x32x16_bf16 v[16:31], v[156:159], v[168:171], v[16:31]
	v_mfma_f32_32x32x16_bf16 v[32:47], v[172:175], v[160:163], v[32:47]
	v_mfma_f32_32x32x16_bf16 v[0:15], v[172:175], v[168:171], v[0:15]
	s_cbranch_scc1 .LBB0_377
	v_add_co_u32_e32 v84, vcc, 0x10000, v144
	global_load_dwordx4 v[68:71], v[144:145], off offset:384
	global_load_dwordx4 v[76:79], v[142:143], off offset:384
	v_addc_co_u32_e32 v85, vcc, 0, v145, vcc
	v_add_co_u32_e32 v92, vcc, 0x10000, v142
	global_load_dwordx4 v[84:87], v[84:85], off offset:384
	s_nop 0
	v_addc_co_u32_e32 v93, vcc, 0, v143, vcc
	v_add_co_u32_e32 v100, vcc, 0x20000, v144
	global_load_dwordx4 v[92:95], v[92:93], off offset:384
	s_nop 0
	v_addc_co_u32_e32 v101, vcc, 0, v145, vcc
	v_add_co_u32_e32 v108, vcc, 0x20000, v142
	global_load_dwordx4 v[100:103], v[100:101], off offset:384
	s_nop 0
	v_addc_co_u32_e32 v109, vcc, 0, v143, vcc
	v_add_co_u32_e32 v116, vcc, 0x30000, v144
	global_load_dwordx4 v[108:111], v[108:109], off offset:384
	s_nop 0
	v_addc_co_u32_e32 v117, vcc, 0, v145, vcc
	v_add_co_u32_e32 v120, vcc, 0x30000, v142
	global_load_dwordx4 v[116:119], v[116:117], off offset:384
	s_nop 0
	v_addc_co_u32_e32 v121, vcc, 0, v143, vcc
	global_load_dwordx4 v[120:123], v[120:121], off offset:384
.LBB0_377:
	ds_read_b128 v[142:145], v140
	ds_read_b128 v[148:151], v141 offset:18432
	ds_read_b128 v[152:155], v140 offset:32
	ds_read_b128 v[156:159], v141 offset:18464
	ds_read_b128 v[160:163], v141 offset:23040
	ds_read_b128 v[164:167], v141 offset:23072
	s_mov_b64 s[8:9], -1
	s_waitcnt lgkmcnt(4)
	v_mfma_f32_32x32x16_bf16 v[48:63], v[142:145], v[148:151], v[48:63]
	s_andn2_b64 vcc, exec, s[6:7]
	s_waitcnt lgkmcnt(1)
	v_mfma_f32_32x32x16_bf16 v[16:31], v[142:145], v[160:163], v[16:31]
	ds_read_b128 v[142:145], v140 offset:4608
	ds_read_b128 v[168:171], v140 offset:4640
	s_waitcnt lgkmcnt(1)
	v_mfma_f32_32x32x16_bf16 v[32:47], v[142:145], v[148:151], v[32:47]
	v_mfma_f32_32x32x16_bf16 v[0:15], v[142:145], v[160:163], v[0:15]
	v_mfma_f32_32x32x16_bf16 v[48:63], v[152:155], v[156:159], v[48:63]
	v_mfma_f32_32x32x16_bf16 v[16:31], v[152:155], v[164:167], v[16:31]
	s_waitcnt lgkmcnt(0)
	v_mfma_f32_32x32x16_bf16 v[32:47], v[168:171], v[156:159], v[32:47]
	ds_read_b128 v[142:145], v140 offset:64
	ds_read_b128 v[148:151], v141 offset:18496
	ds_read_b128 v[152:155], v140 offset:96
	ds_read_b128 v[156:159], v141 offset:18528
	v_mfma_f32_32x32x16_bf16 v[0:15], v[168:171], v[164:167], v[0:15]
	ds_read_b128 v[160:163], v141 offset:23104
	ds_read_b128 v[164:167], v141 offset:23136
	s_waitcnt lgkmcnt(4)
	v_mfma_f32_32x32x16_bf16 v[48:63], v[142:145], v[148:151], v[48:63]
	s_waitcnt lgkmcnt(1)
	v_mfma_f32_32x32x16_bf16 v[16:31], v[142:145], v[160:163], v[16:31]
	ds_read_b128 v[142:145], v140 offset:4672
	ds_read_b128 v[168:171], v140 offset:4704
	s_waitcnt lgkmcnt(0)
	s_barrier
	v_mfma_f32_32x32x16_bf16 v[32:47], v[142:145], v[148:151], v[32:47]
	v_mfma_f32_32x32x16_bf16 v[0:15], v[142:145], v[160:163], v[0:15]
	v_mfma_f32_32x32x16_bf16 v[48:63], v[152:155], v[156:159], v[48:63]
	v_mfma_f32_32x32x16_bf16 v[16:31], v[152:155], v[164:167], v[16:31]
	v_mfma_f32_32x32x16_bf16 v[32:47], v[168:171], v[156:159], v[32:47]
	v_mfma_f32_32x32x16_bf16 v[0:15], v[168:171], v[164:167], v[0:15]
	s_cbranch_vccnz .LBB0_372
	s_add_u32 s4, s4, 0x100
	s_waitcnt vmcnt(8)
	ds_write_b128 v130, v[64:67]
	ds_write_b128 v130, v[72:75] offset:18432
	ds_write_b128 v130, v[80:83] offset:4608
	ds_write_b128 v130, v[88:91] offset:23040
	ds_write_b128 v130, v[96:99] offset:9216
	ds_write_b128 v130, v[104:107] offset:27648
	ds_write_b128 v130, v[112:115] offset:13824
	ds_write_b128 v130, v[124:127] offset:32256
	s_waitcnt lgkmcnt(0)
	s_barrier
	s_addc_u32 s5, s5, 0
	s_add_i32 s12, s12, 2
	s_mov_b64 s[8:9], 0
	s_branch .LBB0_372

.LBB0_497:
	ds_read_b128 v[152:155], v136
	ds_read_b128 v[156:159], v131 offset:18432
	ds_read_b128 v[160:163], v136 offset:32
	ds_read_b128 v[164:167], v131 offset:18464
	ds_read_b128 v[168:171], v131 offset:23040
	ds_read_b128 v[172:175], v131 offset:23072
	s_cmp_gt_u32 s11, 12
	s_waitcnt lgkmcnt(4)
	v_mfma_f32_32x32x16_bf16 v[48:63], v[152:155], v[156:159], v[48:63]
	s_waitcnt lgkmcnt(1)
	v_mfma_f32_32x32x16_bf16 v[16:31], v[152:155], v[168:171], v[16:31]
	ds_read_b128 v[152:155], v136 offset:4608
	ds_read_b128 v[176:179], v136 offset:4640
	s_waitcnt lgkmcnt(1)
	v_mfma_f32_32x32x16_bf16 v[32:47], v[152:155], v[156:159], v[32:47]
	v_mfma_f32_32x32x16_bf16 v[0:15], v[152:155], v[168:171], v[0:15]
	v_mfma_f32_32x32x16_bf16 v[48:63], v[160:163], v[164:167], v[48:63]
	v_mfma_f32_32x32x16_bf16 v[16:31], v[160:163], v[172:175], v[16:31]
	s_waitcnt lgkmcnt(0)
	v_mfma_f32_32x32x16_bf16 v[32:47], v[176:179], v[164:167], v[32:47]
	ds_read_b128 v[152:155], v136 offset:64
	ds_read_b128 v[156:159], v131 offset:18496
	ds_read_b128 v[160:163], v136 offset:96
	ds_read_b128 v[164:167], v131 offset:18528
	v_mfma_f32_32x32x16_bf16 v[0:15], v[176:179], v[172:175], v[0:15]
	ds_read_b128 v[168:171], v131 offset:23104
	ds_read_b128 v[172:175], v131 offset:23136
	s_waitcnt lgkmcnt(4)
	v_mfma_f32_32x32x16_bf16 v[48:63], v[152:155], v[156:159], v[48:63]
	s_waitcnt lgkmcnt(1)
	v_mfma_f32_32x32x16_bf16 v[16:31], v[152:155], v[168:171], v[16:31]
	ds_read_b128 v[152:155], v136 offset:4672
	ds_read_b128 v[176:179], v136 offset:4704
	s_waitcnt lgkmcnt(0)
	s_barrier
	s_cmp_lt_u32 s11, 14
	s_cbranch_scc1 .Lgw2
	s_waitcnt vmcnt(0)
.Lgw2:
	s_waitcnt vmcnt(8)
	s_cmp_gt_u32 s11, 12
	ds_write_b128 v130, v[72:75]
	ds_write_b128 v130, v[76:79] offset:18432
	ds_write_b128 v130, v[88:91] offset:4608
	ds_write_b128 v130, v[92:95] offset:23040
	ds_write_b128 v130, v[104:107] offset:9216
	ds_write_b128 v130, v[108:111] offset:27648
	ds_write_b128 v130, v[120:123] offset:13824
	ds_write_b128 v130, v[124:127] offset:32256
	s_waitcnt lgkmcnt(0)
	v_mfma_f32_32x32x16_bf16 v[32:47], v[152:155], v[156:159], v[32:47]
	s_barrier
	v_mfma_f32_32x32x16_bf16 v[0:15], v[152:155], v[168:171], v[0:15]
	v_mfma_f32_32x32x16_bf16 v[48:63], v[160:163], v[164:167], v[48:63]
	v_mfma_f32_32x32x16_bf16 v[16:31], v[160:163], v[172:175], v[16:31]
	v_mfma_f32_32x32x16_bf16 v[32:47], v[176:179], v[164:167], v[32:47]
	v_mfma_f32_32x32x16_bf16 v[0:15], v[176:179], v[172:175], v[0:15]
	s_cbranch_scc1 .LBB0_499
	v_add_co_u32_e32 v88, vcc, 0x10000, v146
	global_load_dwordx4 v[72:75], v[146:147], off offset:384
	global_load_dwordx4 v[76:79], v[144:145], off offset:384
	v_addc_co_u32_e32 v89, vcc, 0, v147, vcc
	v_add_co_u32_e32 v92, vcc, 0x10000, v144
	global_load_dwordx4 v[88:91], v[88:89], off offset:384
	s_nop 0
	v_addc_co_u32_e32 v93, vcc, 0, v145, vcc
	v_add_co_u32_e32 v104, vcc, 0x20000, v146
	global_load_dwordx4 v[92:95], v[92:93], off offset:384
	s_nop 0
	v_addc_co_u32_e32 v105, vcc, 0, v147, vcc
	v_add_co_u32_e32 v108, vcc, 0x20000, v144
	global_load_dwordx4 v[104:107], v[104:105], off offset:384
	s_nop 0
	v_addc_co_u32_e32 v109, vcc, 0, v145, vcc
	v_add_co_u32_e32 v120, vcc, 0x30000, v146
	global_load_dwordx4 v[108:111], v[108:109], off offset:384
	s_nop 0
	v_addc_co_u32_e32 v121, vcc, 0, v147, vcc
	v_add_co_u32_e32 v124, vcc, 0x30000, v144
	global_load_dwordx4 v[120:123], v[120:121], off offset:384
	s_nop 0
	v_addc_co_u32_e32 v125, vcc, 0, v145, vcc
	global_load_dwordx4 v[124:127], v[124:125], off offset:384
.LBB0_499:
	ds_read_b128 v[144:147], v136
	ds_read_b128 v[152:155], v131 offset:18432
	ds_read_b128 v[156:159], v136 offset:32
	ds_read_b128 v[160:163], v131 offset:18464
	ds_read_b128 v[164:167], v131 offset:23040
	ds_read_b128 v[168:171], v131 offset:23072
	s_mov_b64 s[8:9], -1
	s_waitcnt lgkmcnt(4)
	v_mfma_f32_32x32x16_bf16 v[48:63], v[144:147], v[152:155], v[48:63]
	s_andn2_b64 vcc, exec, s[6:7]
	s_waitcnt lgkmcnt(1)
	v_mfma_f32_32x32x16_bf16 v[16:31], v[144:147], v[164:167], v[16:31]
	ds_read_b128 v[144:147], v136 offset:4608
	ds_read_b128 v[172:175], v136 offset:4640
	s_waitcnt lgkmcnt(1)
	v_mfma_f32_32x32x16_bf16 v[32:47], v[144:147], v[152:155], v[32:47]
	v_mfma_f32_32x32x16_bf16 v[0:15], v[144:147], v[164:167], v[0:15]
	v_mfma_f32_32x32x16_bf16 v[48:63], v[156:159], v[160:163], v[48:63]
	v_mfma_f32_32x32x16_bf16 v[16:31], v[156:159], v[168:171], v[16:31]
	s_waitcnt lgkmcnt(0)
	v_mfma_f32_32x32x16_bf16 v[32:47], v[172:175], v[160:163], v[32:47]
	ds_read_b128 v[144:147], v136 offset:64
	ds_read_b128 v[152:155], v131 offset:18496
	ds_read_b128 v[156:159], v136 offset:96
	ds_read_b128 v[160:163], v131 offset:18528
	v_mfma_f32_32x32x16_bf16 v[0:15], v[172:175], v[168:171], v[0:15]
	ds_read_b128 v[164:167], v131 offset:23104
	ds_read_b128 v[168:171], v131 offset:23136
	s_waitcnt lgkmcnt(4)
	v_mfma_f32_32x32x16_bf16 v[48:63], v[144:147], v[152:155], v[48:63]
	s_waitcnt lgkmcnt(1)
	v_mfma_f32_32x32x16_bf16 v[16:31], v[144:147], v[164:167], v[16:31]
	ds_read_b128 v[144:147], v136 offset:4672
	ds_read_b128 v[172:175], v136 offset:4704
	s_waitcnt lgkmcnt(0)
	s_barrier
	v_mfma_f32_32x32x16_bf16 v[32:47], v[144:147], v[152:155], v[32:47]
	v_mfma_f32_32x32x16_bf16 v[0:15], v[144:147], v[164:167], v[0:15]
	v_mfma_f32_32x32x16_bf16 v[48:63], v[156:159], v[160:163], v[48:63]
	v_mfma_f32_32x32x16_bf16 v[16:31], v[156:159], v[168:171], v[16:31]
	v_mfma_f32_32x32x16_bf16 v[32:47], v[172:175], v[160:163], v[32:47]
	v_mfma_f32_32x32x16_bf16 v[0:15], v[172:175], v[168:171], v[0:15]
	s_cbranch_vccnz .LBB0_494
	s_add_u32 s4, s4, 0x100
	s_addc_u32 s5, s5, 0
	s_add_i32 s11, s11, 2
	s_mov_b64 s[8:9], 0
	s_waitcnt vmcnt(8)
	ds_write_b128 v130, v[64:67]
	ds_write_b128 v130, v[68:71] offset:18432
	ds_write_b128 v130, v[80:83] offset:4608
	ds_write_b128 v130, v[84:87] offset:23040
	ds_write_b128 v130, v[96:99] offset:9216
	ds_write_b128 v130, v[100:103] offset:27648
	ds_write_b128 v130, v[112:115] offset:13824
	ds_write_b128 v130, v[116:119] offset:32256
	s_waitcnt lgkmcnt(0)
	s_barrier
	s_branch .LBB0_494

.LBB0_696:
	s_cmp_lt_u32 s9, 14
	s_cselect_b64 s[12:13], -1, 0
	s_cmp_gt_u32 s9, 13
	v_lshl_add_u64 v[164:165], v[134:135], 0, s[10:11]
	v_lshl_add_u64 v[162:163], v[132:133], 0, s[10:11]
	s_cbranch_scc1 .LBB0_698
	v_add_co_u32_e32 v80, vcc, 0x10000, v164
	global_load_dwordx4 v[64:67], v[164:165], off offset:256
	global_load_dwordx4 v[72:75], v[162:163], off offset:256
	v_addc_co_u32_e32 v81, vcc, 0, v165, vcc
	v_add_co_u32_e32 v88, vcc, 0x10000, v162
	global_load_dwordx4 v[80:83], v[80:81], off offset:256
	s_nop 0
	v_addc_co_u32_e32 v89, vcc, 0, v163, vcc
	v_add_co_u32_e32 v96, vcc, 0x20000, v164
	global_load_dwordx4 v[88:91], v[88:89], off offset:256
	s_nop 0
	v_addc_co_u32_e32 v97, vcc, 0, v165, vcc
	v_add_co_u32_e32 v104, vcc, 0x20000, v162
	global_load_dwordx4 v[96:99], v[96:97], off offset:256
	s_nop 0
	v_addc_co_u32_e32 v105, vcc, 0, v163, vcc
	v_add_co_u32_e32 v112, vcc, 0x30000, v164
	global_load_dwordx4 v[104:107], v[104:105], off offset:256
	s_nop 0
	v_addc_co_u32_e32 v113, vcc, 0, v165, vcc
	v_add_co_u32_e32 v124, vcc, 0x30000, v162
	global_load_dwordx4 v[112:115], v[112:113], off offset:256
	s_nop 0
	v_addc_co_u32_e32 v125, vcc, 0, v163, vcc
	global_load_dwordx4 v[124:127], v[124:125], off offset:256
.LBB0_698:
	ds_read_b128 v[166:169], v140
	ds_read_b128 v[172:175], v141 offset:18432
	ds_read_b128 v[176:179], v140 offset:32
	ds_read_b128 v[180:183], v141 offset:18464
	ds_read_b128 v[184:187], v141 offset:23040
	ds_read_b128 v[188:191], v141 offset:23072
	s_cmp_gt_u32 s9, 12
	s_waitcnt lgkmcnt(4)
	v_mfma_f32_32x32x16_bf16 v[48:63], v[166:169], v[172:175], v[48:63]
	s_waitcnt lgkmcnt(1)
	v_mfma_f32_32x32x16_bf16 v[16:31], v[166:169], v[184:187], v[16:31]
	ds_read_b128 v[166:169], v140 offset:4608
	ds_read_b128 v[196:199], v140 offset:4640
	s_waitcnt lgkmcnt(1)
	v_mfma_f32_32x32x16_bf16 v[32:47], v[166:169], v[172:175], v[32:47]
	v_mfma_f32_32x32x16_bf16 v[0:15], v[166:169], v[184:187], v[0:15]
	v_mfma_f32_32x32x16_bf16 v[48:63], v[176:179], v[180:183], v[48:63]
	v_mfma_f32_32x32x16_bf16 v[16:31], v[176:179], v[188:191], v[16:31]
	s_waitcnt lgkmcnt(0)
	v_mfma_f32_32x32x16_bf16 v[32:47], v[196:199], v[180:183], v[32:47]
	ds_read_b128 v[166:169], v140 offset:64
	ds_read_b128 v[172:175], v141 offset:18496
	ds_read_b128 v[176:179], v140 offset:96
	ds_read_b128 v[180:183], v141 offset:18528
	v_mfma_f32_32x32x16_bf16 v[0:15], v[196:199], v[188:191], v[0:15]
	ds_read_b128 v[184:187], v141 offset:23104
	ds_read_b128 v[188:191], v141 offset:23136
	s_waitcnt lgkmcnt(4)
	v_mfma_f32_32x32x16_bf16 v[48:63], v[166:169], v[172:175], v[48:63]
	s_waitcnt lgkmcnt(1)
	v_mfma_f32_32x32x16_bf16 v[16:31], v[166:169], v[184:187], v[16:31]
	ds_read_b128 v[166:169], v140 offset:4672
	ds_read_b128 v[196:199], v140 offset:4704
	s_waitcnt lgkmcnt(0)
	s_barrier
	s_cmp_lt_u32 s9, 14
	s_cbranch_scc1 .Lgw3
	s_waitcnt vmcnt(0)
.Lgw3:
	s_waitcnt vmcnt(8)
	s_cmp_gt_u32 s9, 12
	ds_write_b128 v130, v[68:71]
	ds_write_b128 v130, v[76:79] offset:18432
	ds_write_b128 v130, v[84:87] offset:4608
	ds_write_b128 v130, v[92:95] offset:23040
	ds_write_b128 v130, v[100:103] offset:9216
	ds_write_b128 v130, v[108:111] offset:27648
	ds_write_b128 v130, v[116:119] offset:13824
	ds_write_b128 v130, v[120:123] offset:32256
	s_waitcnt lgkmcnt(0)
	v_mfma_f32_32x32x16_bf16 v[32:47], v[166:169], v[172:175], v[32:47]
	s_barrier
	v_mfma_f32_32x32x16_bf16 v[0:15], v[166:169], v[184:187], v[0:15]
	v_mfma_f32_32x32x16_bf16 v[48:63], v[176:179], v[180:183], v[48:63]
	v_mfma_f32_32x32x16_bf16 v[16:31], v[176:179], v[188:191], v[16:31]
	v_mfma_f32_32x32x16_bf16 v[32:47], v[196:199], v[180:183], v[32:47]
	v_mfma_f32_32x32x16_bf16 v[0:15], v[196:199], v[188:191], v[0:15]
	s_cbranch_scc1 .LBB0_700
	v_add_co_u32_e32 v84, vcc, 0x10000, v164
	global_load_dwordx4 v[68:71], v[164:165], off offset:384
	global_load_dwordx4 v[76:79], v[162:163], off offset:384
	v_addc_co_u32_e32 v85, vcc, 0, v165, vcc
	v_add_co_u32_e32 v92, vcc, 0x10000, v162
	global_load_dwordx4 v[84:87], v[84:85], off offset:384
	s_nop 0
	v_addc_co_u32_e32 v93, vcc, 0, v163, vcc
	v_add_co_u32_e32 v100, vcc, 0x20000, v164
	global_load_dwordx4 v[92:95], v[92:93], off offset:384
	s_nop 0
	v_addc_co_u32_e32 v101, vcc, 0, v165, vcc
	v_add_co_u32_e32 v108, vcc, 0x20000, v162
	global_load_dwordx4 v[100:103], v[100:101], off offset:384
	s_nop 0
	v_addc_co_u32_e32 v109, vcc, 0, v163, vcc
	v_add_co_u32_e32 v116, vcc, 0x30000, v164
	global_load_dwordx4 v[108:111], v[108:109], off offset:384
	s_nop 0
	v_addc_co_u32_e32 v117, vcc, 0, v165, vcc
	v_add_co_u32_e32 v120, vcc, 0x30000, v162
	global_load_dwordx4 v[116:119], v[116:117], off offset:384
	s_nop 0
	v_addc_co_u32_e32 v121, vcc, 0, v163, vcc
	global_load_dwordx4 v[120:123], v[120:121], off offset:384
.LBB0_700:
	ds_read_b128 v[162:165], v140
	ds_read_b128 v[166:169], v141 offset:18432
	ds_read_b128 v[172:175], v140 offset:32
	ds_read_b128 v[176:179], v141 offset:18464
	ds_read_b128 v[180:183], v141 offset:23040
	ds_read_b128 v[184:187], v141 offset:23072
	s_mov_b64 s[14:15], -1
	s_waitcnt lgkmcnt(4)
	v_mfma_f32_32x32x16_bf16 v[48:63], v[162:165], v[166:169], v[48:63]
	s_andn2_b64 vcc, exec, s[12:13]
	s_waitcnt lgkmcnt(1)
	v_mfma_f32_32x32x16_bf16 v[16:31], v[162:165], v[180:183], v[16:31]
	ds_read_b128 v[162:165], v140 offset:4608
	ds_read_b128 v[188:191], v140 offset:4640
	s_waitcnt lgkmcnt(1)
	v_mfma_f32_32x32x16_bf16 v[32:47], v[162:165], v[166:169], v[32:47]
	v_mfma_f32_32x32x16_bf16 v[0:15], v[162:165], v[180:183], v[0:15]
	v_mfma_f32_32x32x16_bf16 v[48:63], v[172:175], v[176:179], v[48:63]
	v_mfma_f32_32x32x16_bf16 v[16:31], v[172:175], v[184:187], v[16:31]
	s_waitcnt lgkmcnt(0)
	v_mfma_f32_32x32x16_bf16 v[32:47], v[188:191], v[176:179], v[32:47]
	ds_read_b128 v[162:165], v140 offset:64
	ds_read_b128 v[166:169], v141 offset:18496
	ds_read_b128 v[172:175], v140 offset:96
	ds_read_b128 v[176:179], v141 offset:18528
	v_mfma_f32_32x32x16_bf16 v[0:15], v[188:191], v[184:187], v[0:15]
	ds_read_b128 v[180:183], v141 offset:23104
	ds_read_b128 v[184:187], v141 offset:23136
	s_waitcnt lgkmcnt(4)
	v_mfma_f32_32x32x16_bf16 v[48:63], v[162:165], v[166:169], v[48:63]
	s_waitcnt lgkmcnt(1)
	v_mfma_f32_32x32x16_bf16 v[16:31], v[162:165], v[180:183], v[16:31]
	ds_read_b128 v[162:165], v140 offset:4672
	ds_read_b128 v[188:191], v140 offset:4704
	s_waitcnt lgkmcnt(0)
	s_barrier
	v_mfma_f32_32x32x16_bf16 v[32:47], v[162:165], v[166:169], v[32:47]
	v_mfma_f32_32x32x16_bf16 v[0:15], v[162:165], v[180:183], v[0:15]
	v_mfma_f32_32x32x16_bf16 v[48:63], v[172:175], v[176:179], v[48:63]
	v_mfma_f32_32x32x16_bf16 v[16:31], v[172:175], v[184:187], v[16:31]
	v_mfma_f32_32x32x16_bf16 v[32:47], v[188:191], v[176:179], v[32:47]
	v_mfma_f32_32x32x16_bf16 v[0:15], v[188:191], v[184:187], v[0:15]
	s_cbranch_vccnz .LBB0_695
	s_add_u32 s10, s10, 0x100
	s_waitcnt vmcnt(8)
	ds_write_b128 v130, v[64:67]
	ds_write_b128 v130, v[72:75] offset:18432
	ds_write_b128 v130, v[80:83] offset:4608
	ds_write_b128 v130, v[88:91] offset:23040
	ds_write_b128 v130, v[96:99] offset:9216
	ds_write_b128 v130, v[104:107] offset:27648
	ds_write_b128 v130, v[112:115] offset:13824
	ds_write_b128 v130, v[124:127] offset:32256
	s_waitcnt lgkmcnt(0)
	s_barrier
	s_addc_u32 s11, s11, 0
	s_add_i32 s9, s9, 2
	s_mov_b64 s[14:15], 0
	s_branch .LBB0_695

.LBB0_840:
	s_cmp_lt_u32 s13, 14
	s_cselect_b64 s[6:7], -1, 0
	s_cmp_gt_u32 s13, 13
	v_lshl_add_u64 v[144:145], v[134:135], 0, s[4:5]
	v_lshl_add_u64 v[142:143], v[132:133], 0, s[4:5]
	s_cbranch_scc1 .LBB0_842
	v_add_co_u32_e32 v80, vcc, 0x10000, v144
	global_load_dwordx4 v[76:79], v[144:145], off offset:256
	global_load_dwordx4 v[68:71], v[142:143], off offset:256
	v_addc_co_u32_e32 v81, vcc, 0, v145, vcc
	v_add_co_u32_e32 v88, vcc, 0x10000, v142
	global_load_dwordx4 v[80:83], v[80:81], off offset:256
	s_nop 0
	v_addc_co_u32_e32 v89, vcc, 0, v143, vcc
	v_add_co_u32_e32 v96, vcc, 0x20000, v144
	global_load_dwordx4 v[88:91], v[88:89], off offset:256
	s_nop 0
	v_addc_co_u32_e32 v97, vcc, 0, v145, vcc
	v_add_co_u32_e32 v104, vcc, 0x20000, v142
	global_load_dwordx4 v[96:99], v[96:97], off offset:256
	s_nop 0
	v_addc_co_u32_e32 v105, vcc, 0, v143, vcc
	v_add_co_u32_e32 v112, vcc, 0x30000, v144
	global_load_dwordx4 v[104:107], v[104:105], off offset:256
	s_nop 0
	v_addc_co_u32_e32 v113, vcc, 0, v145, vcc
	v_add_co_u32_e32 v124, vcc, 0x30000, v142
	global_load_dwordx4 v[112:115], v[112:113], off offset:256
	s_nop 0
	v_addc_co_u32_e32 v125, vcc, 0, v143, vcc
	global_load_dwordx4 v[124:127], v[124:125], off offset:256
.LBB0_842:
	ds_read_b128 v[146:149], v140
	ds_read_b128 v[150:153], v141 offset:18432
	ds_read_b128 v[154:157], v140 offset:32
	ds_read_b128 v[158:161], v141 offset:18464
	ds_read_b128 v[166:169], v141 offset:23040
	ds_read_b128 v[170:173], v141 offset:23072
	s_cmp_gt_u32 s13, 12
	s_waitcnt lgkmcnt(4)
	v_mfma_f32_32x32x16_bf16 v[48:63], v[146:149], v[150:153], v[48:63]
	s_waitcnt lgkmcnt(1)
	v_mfma_f32_32x32x16_bf16 v[16:31], v[146:149], v[166:169], v[16:31]
	ds_read_b128 v[146:149], v140 offset:4608
	ds_read_b128 v[174:177], v140 offset:4640
	s_waitcnt lgkmcnt(1)
	v_mfma_f32_32x32x16_bf16 v[32:47], v[146:149], v[150:153], v[32:47]
	v_mfma_f32_32x32x16_bf16 v[0:15], v[146:149], v[166:169], v[0:15]
	v_mfma_f32_32x32x16_bf16 v[48:63], v[154:157], v[158:161], v[48:63]
	v_mfma_f32_32x32x16_bf16 v[16:31], v[154:157], v[170:173], v[16:31]
	s_waitcnt lgkmcnt(0)
	v_mfma_f32_32x32x16_bf16 v[32:47], v[174:177], v[158:161], v[32:47]
	ds_read_b128 v[146:149], v140 offset:64
	ds_read_b128 v[150:153], v141 offset:18496
	ds_read_b128 v[154:157], v140 offset:96
	ds_read_b128 v[158:161], v141 offset:18528
	v_mfma_f32_32x32x16_bf16 v[0:15], v[174:177], v[170:173], v[0:15]
	ds_read_b128 v[166:169], v141 offset:23104
	ds_read_b128 v[170:173], v141 offset:23136
	s_waitcnt lgkmcnt(4)
	v_mfma_f32_32x32x16_bf16 v[48:63], v[146:149], v[150:153], v[48:63]
	s_waitcnt lgkmcnt(1)
	v_mfma_f32_32x32x16_bf16 v[16:31], v[146:149], v[166:169], v[16:31]
	ds_read_b128 v[146:149], v140 offset:4672
	ds_read_b128 v[174:177], v140 offset:4704
	s_waitcnt lgkmcnt(0)
	s_barrier
	s_cmp_lt_u32 s13, 14
	s_cbranch_scc1 .Lgw4
	s_waitcnt vmcnt(0)
.Lgw4:
	s_waitcnt vmcnt(8)
	s_cmp_gt_u32 s13, 12
	ds_write_b128 v130, v[64:67]
	ds_write_b128 v130, v[72:75] offset:18432
	ds_write_b128 v130, v[84:87] offset:4608
	ds_write_b128 v130, v[92:95] offset:23040
	ds_write_b128 v130, v[100:103] offset:9216
	ds_write_b128 v130, v[108:111] offset:27648
	ds_write_b128 v130, v[116:119] offset:13824
	ds_write_b128 v130, v[120:123] offset:32256
	s_waitcnt lgkmcnt(0)
	v_mfma_f32_32x32x16_bf16 v[32:47], v[146:149], v[150:153], v[32:47]
	s_barrier
	v_mfma_f32_32x32x16_bf16 v[0:15], v[146:149], v[166:169], v[0:15]
	v_mfma_f32_32x32x16_bf16 v[48:63], v[154:157], v[158:161], v[48:63]
	v_mfma_f32_32x32x16_bf16 v[16:31], v[154:157], v[170:173], v[16:31]
	v_mfma_f32_32x32x16_bf16 v[32:47], v[174:177], v[158:161], v[32:47]
	v_mfma_f32_32x32x16_bf16 v[0:15], v[174:177], v[170:173], v[0:15]
	s_cbranch_scc1 .LBB0_844
	v_add_co_u32_e32 v84, vcc, 0x10000, v144
	global_load_dwordx4 v[64:67], v[144:145], off offset:384
	global_load_dwordx4 v[72:75], v[142:143], off offset:384
	v_addc_co_u32_e32 v85, vcc, 0, v145, vcc
	v_add_co_u32_e32 v92, vcc, 0x10000, v142
	global_load_dwordx4 v[84:87], v[84:85], off offset:384
	s_nop 0
	v_addc_co_u32_e32 v93, vcc, 0, v143, vcc
	v_add_co_u32_e32 v100, vcc, 0x20000, v144
	global_load_dwordx4 v[92:95], v[92:93], off offset:384
	s_nop 0
	v_addc_co_u32_e32 v101, vcc, 0, v145, vcc
	v_add_co_u32_e32 v108, vcc, 0x20000, v142
	global_load_dwordx4 v[100:103], v[100:101], off offset:384
	s_nop 0
	v_addc_co_u32_e32 v109, vcc, 0, v143, vcc
	v_add_co_u32_e32 v116, vcc, 0x30000, v144
	global_load_dwordx4 v[108:111], v[108:109], off offset:384
	s_nop 0
	v_addc_co_u32_e32 v117, vcc, 0, v145, vcc
	v_add_co_u32_e32 v120, vcc, 0x30000, v142
	global_load_dwordx4 v[116:119], v[116:117], off offset:384
	s_nop 0
	v_addc_co_u32_e32 v121, vcc, 0, v143, vcc
	global_load_dwordx4 v[120:123], v[120:121], off offset:384
.LBB0_844:
	ds_read_b128 v[142:145], v140
	ds_read_b128 v[146:149], v141 offset:18432
	ds_read_b128 v[150:153], v140 offset:32
	ds_read_b128 v[154:157], v141 offset:18464
	ds_read_b128 v[158:161], v141 offset:23040
	ds_read_b128 v[166:169], v141 offset:23072
	s_mov_b64 s[8:9], -1
	s_waitcnt lgkmcnt(4)
	v_mfma_f32_32x32x16_bf16 v[48:63], v[142:145], v[146:149], v[48:63]
	s_andn2_b64 vcc, exec, s[6:7]
	s_waitcnt lgkmcnt(1)
	v_mfma_f32_32x32x16_bf16 v[16:31], v[142:145], v[158:161], v[16:31]
	ds_read_b128 v[142:145], v140 offset:4608
	ds_read_b128 v[170:173], v140 offset:4640
	s_waitcnt lgkmcnt(1)
	v_mfma_f32_32x32x16_bf16 v[32:47], v[142:145], v[146:149], v[32:47]
	v_mfma_f32_32x32x16_bf16 v[0:15], v[142:145], v[158:161], v[0:15]
	v_mfma_f32_32x32x16_bf16 v[48:63], v[150:153], v[154:157], v[48:63]
	v_mfma_f32_32x32x16_bf16 v[16:31], v[150:153], v[166:169], v[16:31]
	s_waitcnt lgkmcnt(0)
	v_mfma_f32_32x32x16_bf16 v[32:47], v[170:173], v[154:157], v[32:47]
	ds_read_b128 v[142:145], v140 offset:64
	ds_read_b128 v[146:149], v141 offset:18496
	ds_read_b128 v[150:153], v140 offset:96
	ds_read_b128 v[154:157], v141 offset:18528
	v_mfma_f32_32x32x16_bf16 v[0:15], v[170:173], v[166:169], v[0:15]
	ds_read_b128 v[158:161], v141 offset:23104
	ds_read_b128 v[166:169], v141 offset:23136
	s_waitcnt lgkmcnt(4)
	v_mfma_f32_32x32x16_bf16 v[48:63], v[142:145], v[146:149], v[48:63]
	s_waitcnt lgkmcnt(1)
	v_mfma_f32_32x32x16_bf16 v[16:31], v[142:145], v[158:161], v[16:31]
	ds_read_b128 v[142:145], v140 offset:4672
	ds_read_b128 v[170:173], v140 offset:4704
	s_waitcnt lgkmcnt(0)
	s_barrier
	v_mfma_f32_32x32x16_bf16 v[32:47], v[142:145], v[146:149], v[32:47]
	v_mfma_f32_32x32x16_bf16 v[0:15], v[142:145], v[158:161], v[0:15]
	v_mfma_f32_32x32x16_bf16 v[48:63], v[150:153], v[154:157], v[48:63]
	v_mfma_f32_32x32x16_bf16 v[16:31], v[150:153], v[166:169], v[16:31]
	v_mfma_f32_32x32x16_bf16 v[32:47], v[170:173], v[154:157], v[32:47]
	v_mfma_f32_32x32x16_bf16 v[0:15], v[170:173], v[166:169], v[0:15]
	s_cbranch_vccnz .LBB0_839
	s_add_u32 s4, s4, 0x100
	s_waitcnt vmcnt(8)
	ds_write_b128 v130, v[76:79]
	ds_write_b128 v130, v[68:71] offset:18432
	ds_write_b128 v130, v[80:83] offset:4608
	ds_write_b128 v130, v[88:91] offset:23040
	ds_write_b128 v130, v[96:99] offset:9216
	ds_write_b128 v130, v[104:107] offset:27648
	ds_write_b128 v130, v[112:115] offset:13824
	ds_write_b128 v130, v[124:127] offset:32256
	s_waitcnt lgkmcnt(0)
	s_barrier
	s_addc_u32 s5, s5, 0
	s_add_i32 s13, s13, 2
	s_mov_b64 s[8:9], 0
	s_branch .LBB0_839

.LBB0_964:
	ds_read_b128 v[152:155], v136
	ds_read_b128 v[156:159], v131 offset:18432
	ds_read_b128 v[160:163], v136 offset:32
	ds_read_b128 v[164:167], v131 offset:18464
	ds_read_b128 v[168:171], v131 offset:23040
	ds_read_b128 v[172:175], v131 offset:23072
	s_cmp_gt_u32 s9, 12
	s_waitcnt lgkmcnt(4)
	v_mfma_f32_32x32x16_bf16 v[48:63], v[152:155], v[156:159], v[48:63]
	s_waitcnt lgkmcnt(1)
	v_mfma_f32_32x32x16_bf16 v[16:31], v[152:155], v[168:171], v[16:31]
	ds_read_b128 v[152:155], v136 offset:4608
	ds_read_b128 v[176:179], v136 offset:4640
	s_waitcnt lgkmcnt(1)
	v_mfma_f32_32x32x16_bf16 v[32:47], v[152:155], v[156:159], v[32:47]
	v_mfma_f32_32x32x16_bf16 v[0:15], v[152:155], v[168:171], v[0:15]
	v_mfma_f32_32x32x16_bf16 v[48:63], v[160:163], v[164:167], v[48:63]
	v_mfma_f32_32x32x16_bf16 v[16:31], v[160:163], v[172:175], v[16:31]
	s_waitcnt lgkmcnt(0)
	v_mfma_f32_32x32x16_bf16 v[32:47], v[176:179], v[164:167], v[32:47]
	ds_read_b128 v[152:155], v136 offset:64
	ds_read_b128 v[156:159], v131 offset:18496
	ds_read_b128 v[160:163], v136 offset:96
	ds_read_b128 v[164:167], v131 offset:18528
	v_mfma_f32_32x32x16_bf16 v[0:15], v[176:179], v[172:175], v[0:15]
	ds_read_b128 v[168:171], v131 offset:23104
	ds_read_b128 v[172:175], v131 offset:23136
	s_waitcnt lgkmcnt(4)
	v_mfma_f32_32x32x16_bf16 v[48:63], v[152:155], v[156:159], v[48:63]
	s_waitcnt lgkmcnt(1)
	v_mfma_f32_32x32x16_bf16 v[16:31], v[152:155], v[168:171], v[16:31]
	ds_read_b128 v[152:155], v136 offset:4672
	ds_read_b128 v[176:179], v136 offset:4704
	s_waitcnt lgkmcnt(0)
	s_barrier
	s_cmp_lt_u32 s9, 14
	s_cbranch_scc1 .Lgw5
	s_waitcnt vmcnt(0)
.Lgw5:
	s_waitcnt vmcnt(8)
	s_cmp_gt_u32 s9, 12
	ds_write_b128 v130, v[72:75]
	ds_write_b128 v130, v[76:79] offset:18432
	ds_write_b128 v130, v[88:91] offset:4608
	ds_write_b128 v130, v[92:95] offset:23040
	ds_write_b128 v130, v[104:107] offset:9216
	ds_write_b128 v130, v[108:111] offset:27648
	ds_write_b128 v130, v[124:127] offset:13824
	ds_write_b128 v130, v[120:123] offset:32256
	s_waitcnt lgkmcnt(0)
	v_mfma_f32_32x32x16_bf16 v[32:47], v[152:155], v[156:159], v[32:47]
	s_barrier
	v_mfma_f32_32x32x16_bf16 v[0:15], v[152:155], v[168:171], v[0:15]
	v_mfma_f32_32x32x16_bf16 v[48:63], v[160:163], v[164:167], v[48:63]
	v_mfma_f32_32x32x16_bf16 v[16:31], v[160:163], v[172:175], v[16:31]
	v_mfma_f32_32x32x16_bf16 v[32:47], v[176:179], v[164:167], v[32:47]
	v_mfma_f32_32x32x16_bf16 v[0:15], v[176:179], v[172:175], v[0:15]
	s_cbranch_scc1 .LBB0_966
	v_add_co_u32_e32 v88, vcc, 0x10000, v146
	global_load_dwordx4 v[72:75], v[146:147], off offset:384
	global_load_dwordx4 v[76:79], v[144:145], off offset:384
	v_addc_co_u32_e32 v89, vcc, 0, v147, vcc
	v_add_co_u32_e32 v92, vcc, 0x10000, v144
	global_load_dwordx4 v[88:91], v[88:89], off offset:384
	s_nop 0
	v_addc_co_u32_e32 v93, vcc, 0, v145, vcc
	v_add_co_u32_e32 v104, vcc, 0x20000, v146
	global_load_dwordx4 v[92:95], v[92:93], off offset:384
	s_nop 0
	v_addc_co_u32_e32 v105, vcc, 0, v147, vcc
	v_add_co_u32_e32 v108, vcc, 0x20000, v144
	global_load_dwordx4 v[104:107], v[104:105], off offset:384
	s_nop 0
	v_addc_co_u32_e32 v109, vcc, 0, v145, vcc
	v_add_co_u32_e32 v120, vcc, 0x30000, v146
	global_load_dwordx4 v[108:111], v[108:109], off offset:384
	s_nop 0
	v_addc_co_u32_e32 v121, vcc, 0, v147, vcc
	global_load_dwordx4 v[124:127], v[120:121], off offset:384
	v_add_co_u32_e32 v120, vcc, 0x30000, v144
	s_nop 1
	v_addc_co_u32_e32 v121, vcc, 0, v145, vcc
	global_load_dwordx4 v[120:123], v[120:121], off offset:384
.LBB0_966:
	ds_read_b128 v[144:147], v136
	ds_read_b128 v[152:155], v131 offset:18432
	ds_read_b128 v[156:159], v136 offset:32
	ds_read_b128 v[160:163], v131 offset:18464
	ds_read_b128 v[164:167], v131 offset:23040
	ds_read_b128 v[168:171], v131 offset:23072
	s_mov_b64 s[6:7], -1
	s_waitcnt lgkmcnt(4)
	v_mfma_f32_32x32x16_bf16 v[48:63], v[144:147], v[152:155], v[48:63]
	s_andn2_b64 vcc, exec, s[4:5]
	s_waitcnt lgkmcnt(1)
	v_mfma_f32_32x32x16_bf16 v[16:31], v[144:147], v[164:167], v[16:31]
	ds_read_b128 v[144:147], v136 offset:4608
	ds_read_b128 v[172:175], v136 offset:4640
	s_waitcnt lgkmcnt(1)
	v_mfma_f32_32x32x16_bf16 v[32:47], v[144:147], v[152:155], v[32:47]
	v_mfma_f32_32x32x16_bf16 v[0:15], v[144:147], v[164:167], v[0:15]
	v_mfma_f32_32x32x16_bf16 v[48:63], v[156:159], v[160:163], v[48:63]
	v_mfma_f32_32x32x16_bf16 v[16:31], v[156:159], v[168:171], v[16:31]
	s_waitcnt lgkmcnt(0)
	v_mfma_f32_32x32x16_bf16 v[32:47], v[172:175], v[160:163], v[32:47]
	ds_read_b128 v[144:147], v136 offset:64
	ds_read_b128 v[152:155], v131 offset:18496
	ds_read_b128 v[156:159], v136 offset:96
	ds_read_b128 v[160:163], v131 offset:18528
	v_mfma_f32_32x32x16_bf16 v[0:15], v[172:175], v[168:171], v[0:15]
	ds_read_b128 v[164:167], v131 offset:23104
	ds_read_b128 v[168:171], v131 offset:23136
	s_waitcnt lgkmcnt(4)
	v_mfma_f32_32x32x16_bf16 v[48:63], v[144:147], v[152:155], v[48:63]
	s_waitcnt lgkmcnt(1)
	v_mfma_f32_32x32x16_bf16 v[16:31], v[144:147], v[164:167], v[16:31]
	ds_read_b128 v[144:147], v136 offset:4672
	ds_read_b128 v[172:175], v136 offset:4704
	s_waitcnt lgkmcnt(0)
	s_barrier
	v_mfma_f32_32x32x16_bf16 v[32:47], v[144:147], v[152:155], v[32:47]
	v_mfma_f32_32x32x16_bf16 v[0:15], v[144:147], v[164:167], v[0:15]
	v_mfma_f32_32x32x16_bf16 v[48:63], v[156:159], v[160:163], v[48:63]
	v_mfma_f32_32x32x16_bf16 v[16:31], v[156:159], v[168:171], v[16:31]
	v_mfma_f32_32x32x16_bf16 v[32:47], v[172:175], v[160:163], v[32:47]
	v_mfma_f32_32x32x16_bf16 v[0:15], v[172:175], v[168:171], v[0:15]
	s_cbranch_vccnz .LBB0_961
	s_add_u32 s0, s0, 0x100
	s_addc_u32 s1, s1, 0
	s_add_i32 s9, s9, 2
	s_mov_b64 s[6:7], 0
	s_waitcnt vmcnt(8)
	ds_write_b128 v130, v[64:67]
	ds_write_b128 v130, v[68:71] offset:18432
	ds_write_b128 v130, v[80:83] offset:4608
	ds_write_b128 v130, v[84:87] offset:23040
	ds_write_b128 v130, v[96:99] offset:9216
	ds_write_b128 v130, v[100:103] offset:27648
	ds_write_b128 v130, v[112:115] offset:13824
	ds_write_b128 v130, v[116:119] offset:32256
	s_waitcnt lgkmcnt(0)
	s_barrier
	s_branch .LBB0_961
